# P0 prologue: non-temporal (nt) loads for the read-once f32 inputs (weights, x, p)
# speedup vs baseline: 1.0494x; 1.0464x over previous
; __device__ __forceinline__ TRegs t_load(const TItem& t, int lane) {
;     const int nblk = t.N / 32, kb = t.item / nblk, nb = t.item % nblk, k0 = 64 * kb, n0 = 32 * nb; TRegs r;
;     const float* p = t.W + (size_t)(k0 + (lane >> 3)) * t.N + n0 + 4 * (lane & 7);
; #pragma unroll
;     for (int i = 0; i < 8; ++i) r.v[i] = *(const f32x4*)(p + (size_t)(8 * i) * t.N);
;     if (t.gk) {
; #pragma unroll
;         for (int i = 0; i < 8; ++i) r.v[i] = r.v[i] * t.gk[k0 + (lane >> 3) + 8 * i];
;     }
.LBB0_100:
	s_lshr_b32 s5, s14, 5
	v_cvt_f32_u32_e32 v0, s5
	s_sub_i32 s38, 0, s5
	s_abs_i32 s21, s4
	s_ashr_i32 s11, s4, 31
	v_rcp_iflag_f32_e32 v0, v0
	v_and_b32_e32 v2, 63, v192
	v_lshrrev_b32_e32 v129, 3, v2
	s_mov_b32 s15, 0
	v_mul_f32_e32 v0, 0x4f7ffffe, v0
	v_cvt_u32_f32_e32 v0, v0
	v_mov_b32_e32 v131, 0
	v_readfirstlane_b32 s48, v0
	s_mul_i32 s38, s38, s48
	s_mul_hi_u32 s38, s48, s38
	s_add_i32 s48, s48, s38
	s_mul_hi_u32 s38, s21, s48
	s_mul_i32 s48, s38, s5
	s_sub_i32 s21, s21, s48
	s_add_i32 s49, s38, 1
	s_sub_i32 s48, s21, s5
	s_cmp_ge_u32 s21, s5
	s_cselect_b32 s38, s49, s38
	s_cselect_b32 s21, s48, s21
	s_add_i32 s48, s38, 1
	s_cmp_ge_u32 s21, s5
	s_cselect_b32 s21, s48, s38
	s_xor_b32 s21, s21, s11
	s_sub_i32 s11, s21, s11
	v_lshl_or_b32 v28, s11, 6, v129
	v_mad_u64_u32 v[0:1], s[50:51], v28, s14, 0
	s_mul_i32 s5, s11, s5
	v_ashrrev_i32_e32 v29, 31, v28
	v_mov_b32_e32 v2, v1
	s_sub_i32 s5, s4, s5
	v_mad_u64_u32 v[2:3], s[50:51], v29, s14, v[2:3]
	s_lshl_b32 s48, s5, 5
	v_mov_b32_e32 v1, v2
	v_lshlrev_b32_e32 v2, 2, v192
	s_waitcnt lgkmcnt(0)
	v_lshl_add_u64 v[0:1], v[0:1], 2, s[46:47]
	s_ashr_i32 s49, s48, 31
	v_and_b32_e32 v66, 28, v2
	v_lshl_add_u64 v[0:1], s[48:49], 2, v[0:1]
	v_lshlrev_b32_e32 v130, 2, v66
	v_lshl_add_u64 v[0:1], v[0:1], 0, v[130:131]
	s_lshl_b64 s[46:47], s[14:15], 5
	v_lshl_add_u64 v[2:3], v[0:1], 0, s[46:47]
	global_load_dwordx4 v[56:59], v[0:1], off nt
	global_load_dwordx4 v[16:19], v[2:3], off nt
	v_lshl_add_u64 v[0:1], v[2:3], 0, s[46:47]
	v_lshl_add_u64 v[2:3], v[0:1], 0, s[46:47]
	global_load_dwordx4 v[24:27], v[0:1], off nt
	global_load_dwordx4 v[12:15], v[2:3], off nt
	v_lshl_add_u64 v[0:1], v[2:3], 0, s[46:47]
	v_lshl_add_u64 v[2:3], v[0:1], 0, s[46:47]
	global_load_dwordx4 v[20:23], v[0:1], off nt
	global_load_dwordx4 v[8:11], v[2:3], off nt
	v_lshl_add_u64 v[0:1], v[2:3], 0, s[46:47]
	global_load_dwordx4 v[4:7], v[0:1], off nt
	v_lshl_add_u64 v[0:1], v[0:1], 0, s[46:47]
	global_load_dwordx4 v[0:3], v[0:1], off nt
	s_load_dwordx2 s[42:43], s[42:43], 0x0
	s_cmp_eq_u64 s[36:37], 0
	s_cbranch_scc1 .LBB0_102
	v_lshl_add_u64 v[28:29], v[28:29], 2, s[36:37]
	global_load_dword v30, v[28:29], off
	global_load_dword v32, v[28:29], off offset:32
	global_load_dword v34, v[28:29], off offset:64
	global_load_dword v36, v[28:29], off offset:96
	global_load_dword v38, v[28:29], off offset:128
	global_load_dword v40, v[28:29], off offset:160
	global_load_dword v42, v[28:29], off offset:192
	global_load_dword v44, v[28:29], off offset:224
	s_waitcnt vmcnt(7)
	v_pk_mul_f32 v[58:59], v[58:59], v[30:31] op_sel_hi:[1,0]
	v_pk_mul_f32 v[56:57], v[56:57], v[30:31] op_sel_hi:[1,0]
	s_waitcnt vmcnt(6)
	v_pk_mul_f32 v[18:19], v[18:19], v[32:33] op_sel_hi:[1,0]
	v_pk_mul_f32 v[16:17], v[16:17], v[32:33] op_sel_hi:[1,0]
	s_waitcnt vmcnt(5)
	v_pk_mul_f32 v[26:27], v[26:27], v[34:35] op_sel_hi:[1,0]
	v_pk_mul_f32 v[24:25], v[24:25], v[34:35] op_sel_hi:[1,0]
	s_waitcnt vmcnt(4)
	v_pk_mul_f32 v[14:15], v[14:15], v[36:37] op_sel_hi:[1,0]
	v_pk_mul_f32 v[12:13], v[12:13], v[36:37] op_sel_hi:[1,0]
	s_waitcnt vmcnt(3)
	v_pk_mul_f32 v[22:23], v[22:23], v[38:39] op_sel_hi:[1,0]
	v_pk_mul_f32 v[20:21], v[20:21], v[38:39] op_sel_hi:[1,0]
	s_waitcnt vmcnt(2)
	v_pk_mul_f32 v[10:11], v[10:11], v[40:41] op_sel_hi:[1,0]
	v_pk_mul_f32 v[8:9], v[8:9], v[40:41] op_sel_hi:[1,0]
	s_waitcnt vmcnt(1)
	v_pk_mul_f32 v[6:7], v[6:7], v[42:43] op_sel_hi:[1,0]
	v_pk_mul_f32 v[4:5], v[4:5], v[42:43] op_sel_hi:[1,0]
	s_waitcnt vmcnt(0)
	v_pk_mul_f32 v[2:3], v[2:3], v[44:45] op_sel_hi:[1,0]
	v_pk_mul_f32 v[0:1], v[0:1], v[44:45] op_sel_hi:[1,0]
; __device__ __forceinline__ TRegs t_load(const TItem& t, int lane) {
;     const int nblk = t.N / 32, kb = t.item / nblk, nb = t.item % nblk, k0 = 64 * kb, n0 = 32 * nb; TRegs r;
;     const float* p = t.W + (size_t)(k0 + (lane >> 3)) * t.N + n0 + 4 * (lane & 7);
; #pragma unroll
;     for (int i = 0; i < 8; ++i) r.v[i] = *(const f32x4*)(p + (size_t)(8 * i) * t.N);
;     if (t.gk) {
; #pragma unroll
;         for (int i = 0; i < 8; ++i) r.v[i] = r.v[i] * t.gk[k0 + (lane >> 3) + 8 * i];
;     }
.LBB0_102:
	s_lshr_b32 s5, s20, 5
	v_cvt_f32_u32_e32 v28, s5
	s_mov_b32 s21, s15
	s_sub_i32 s15, 0, s5
	s_abs_i32 s36, s33
	v_rcp_iflag_f32_e32 v28, v28
	s_ashr_i32 s11, s33, 31
	v_mul_f32_e32 v28, 0x4f7ffffe, v28
	v_cvt_u32_f32_e32 v28, v28
	s_nop 0
	v_readfirstlane_b32 s37, v28
	s_mul_i32 s15, s15, s37
	s_mul_hi_u32 s15, s37, s15
	s_add_i32 s37, s37, s15
	s_mul_hi_u32 s15, s36, s37
	s_mul_i32 s37, s15, s5
	s_sub_i32 s36, s36, s37
	s_add_i32 s38, s15, 1
	s_sub_i32 s37, s36, s5
	s_cmp_ge_u32 s36, s5
	s_cselect_b32 s15, s38, s15
	s_cselect_b32 s36, s37, s36
	s_add_i32 s37, s15, 1
	s_cmp_ge_u32 s36, s5
	s_cselect_b32 s15, s37, s15
	s_xor_b32 s15, s15, s11
	s_sub_i32 s11, s15, s11
	v_lshl_or_b32 v64, s11, 6, v129
	v_mad_u64_u32 v[28:29], s[46:47], v64, s20, 0
	s_mul_i32 s5, s11, s5
	v_ashrrev_i32_e32 v65, 31, v64
	v_mov_b32_e32 v30, v29
	s_sub_i32 s5, s33, s5
	v_mad_u64_u32 v[30:31], s[46:47], v65, s20, v[30:31]
	s_lshl_b32 s36, s5, 5
	v_mov_b32_e32 v29, v30
	s_waitcnt lgkmcnt(0)
	v_lshl_add_u64 v[28:29], v[28:29], 2, s[42:43]
	s_ashr_i32 s37, s36, 31
	v_lshl_add_u64 v[28:29], s[36:37], 2, v[28:29]
	v_lshl_add_u64 v[32:33], v[28:29], 0, v[130:131]
	s_lshl_b64 s[36:37], s[20:21], 5
	v_lshl_add_u64 v[34:35], v[32:33], 0, s[36:37]
	v_lshl_add_u64 v[40:41], v[34:35], 0, s[36:37]
	v_lshl_add_u64 v[42:43], v[40:41], 0, s[36:37]
	v_lshl_add_u64 v[48:49], v[42:43], 0, s[36:37]
	v_lshl_add_u64 v[50:51], v[48:49], 0, s[36:37]
	v_lshl_add_u64 v[52:53], v[50:51], 0, s[36:37]
	global_load_dwordx4 v[60:63], v[32:33], off nt
	global_load_dwordx4 v[28:31], v[34:35], off nt
	s_nop 0
	global_load_dwordx4 v[32:35], v[40:41], off nt
	global_load_dwordx4 v[36:39], v[42:43], off nt
	s_nop 0
	global_load_dwordx4 v[40:43], v[48:49], off nt
	global_load_dwordx4 v[44:47], v[50:51], off nt
	s_cmp_eq_u64 s[40:41], 0
	global_load_dwordx4 v[48:51], v[52:53], off nt
	v_lshl_add_u64 v[52:53], v[52:53], 0, s[36:37]
	global_load_dwordx4 v[52:55], v[52:53], off nt
	s_cbranch_scc1 .LBB0_104
	v_lshl_add_u64 v[64:65], v[64:65], 2, s[40:41]
	global_load_dword v68, v[64:65], off
	global_load_dword v70, v[64:65], off offset:32
	global_load_dword v72, v[64:65], off offset:64
	global_load_dword v74, v[64:65], off offset:96
	global_load_dword v76, v[64:65], off offset:128
	global_load_dword v78, v[64:65], off offset:160
	global_load_dword v80, v[64:65], off offset:192
	global_load_dword v82, v[64:65], off offset:224
	s_waitcnt vmcnt(7)
	v_pk_mul_f32 v[62:63], v[62:63], v[68:69] op_sel_hi:[1,0]
	v_pk_mul_f32 v[60:61], v[60:61], v[68:69] op_sel_hi:[1,0]
	s_waitcnt vmcnt(6)
	v_pk_mul_f32 v[30:31], v[30:31], v[70:71] op_sel_hi:[1,0]
	v_pk_mul_f32 v[28:29], v[28:29], v[70:71] op_sel_hi:[1,0]
	s_waitcnt vmcnt(5)
	v_pk_mul_f32 v[34:35], v[34:35], v[72:73] op_sel_hi:[1,0]
	v_pk_mul_f32 v[32:33], v[32:33], v[72:73] op_sel_hi:[1,0]
	s_waitcnt vmcnt(4)
	v_pk_mul_f32 v[38:39], v[38:39], v[74:75] op_sel_hi:[1,0]
	v_pk_mul_f32 v[36:37], v[36:37], v[74:75] op_sel_hi:[1,0]
	s_waitcnt vmcnt(3)
	v_pk_mul_f32 v[42:43], v[42:43], v[76:77] op_sel_hi:[1,0]
	v_pk_mul_f32 v[40:41], v[40:41], v[76:77] op_sel_hi:[1,0]
	s_waitcnt vmcnt(2)
	v_pk_mul_f32 v[46:47], v[46:47], v[78:79] op_sel_hi:[1,0]
	v_pk_mul_f32 v[44:45], v[44:45], v[78:79] op_sel_hi:[1,0]
	s_waitcnt vmcnt(1)
	v_pk_mul_f32 v[50:51], v[50:51], v[80:81] op_sel_hi:[1,0]
	v_pk_mul_f32 v[48:49], v[48:49], v[80:81] op_sel_hi:[1,0]
	s_waitcnt vmcnt(0)
	v_pk_mul_f32 v[54:55], v[54:55], v[82:83] op_sel_hi:[1,0]
	v_pk_mul_f32 v[52:53], v[52:53], v[82:83] op_sel_hi:[1,0]

; __device__ __forceinline__ TRegs t_load(const TItem& t, int lane) {
;     const int nblk = t.N / 32, kb = t.item / nblk, nb = t.item % nblk, k0 = 64 * kb, n0 = 32 * nb; TRegs r;
;     const float* p = t.W + (size_t)(k0 + (lane >> 3)) * t.N + n0 + 4 * (lane & 7);
; #pragma unroll
;     for (int i = 0; i < 8; ++i) r.v[i] = *(const f32x4*)(p + (size_t)(8 * i) * t.N);
;     if (t.gk) {
; #pragma unroll
;         for (int i = 0; i < 8; ++i) r.v[i] = r.v[i] * t.gk[k0 + (lane >> 3) + 8 * i];
;     }
.LBB0_177:
	s_lshr_b32 s53, s22, 5
	v_cvt_f32_u32_e32 v64, s53
	s_sub_i32 s97, 0, s53
	s_abs_i32 s96, s11
	s_ashr_i32 s87, s11, 31
	v_rcp_iflag_f32_e32 v64, v64
	s_nop 0
	v_mul_f32_e32 v64, 0x4f7ffffe, v64
	v_cvt_u32_f32_e32 v64, v64
	s_nop 0
	v_readfirstlane_b32 vcc_lo, v64
	s_mul_i32 s97, s97, vcc_lo
	s_mul_hi_u32 s97, vcc_lo, s97
	s_add_i32 vcc_lo, vcc_lo, s97
	s_mul_hi_u32 s97, s96, vcc_lo
	s_mul_i32 vcc_lo, s97, s53
	s_sub_i32 s96, s96, vcc_lo
	s_add_i32 vcc_hi, s97, 1
	s_sub_i32 vcc_lo, s96, s53
	s_cmp_ge_u32 s96, s53
	s_cselect_b32 s97, vcc_hi, s97
	s_cselect_b32 s96, vcc_lo, s96
	s_add_i32 vcc_lo, s97, 1
	s_cmp_ge_u32 s96, s53
	s_cselect_b32 s96, vcc_lo, s97
	s_xor_b32 s96, s96, s87
	s_sub_i32 s87, s96, s87
	v_lshl_or_b32 v96, s87, 6, v129
	v_mad_u64_u32 v[64:65], s[96:97], v96, s22, 0
	s_mul_i32 s53, s87, s53
	v_ashrrev_i32_e32 v97, 31, v96
	v_mov_b32_e32 v66, v65
	s_sub_i32 s53, s11, s53
	v_mad_u64_u32 v[66:67], vcc, v97, s22, v[66:67]
	s_lshl_b32 s96, s53, 5
	v_mov_b32_e32 v65, v66
	s_waitcnt lgkmcnt(0)
	v_lshl_add_u64 v[64:65], v[64:65], 2, s[92:93]
	s_ashr_i32 s97, s96, 31
	v_lshl_add_u64 v[64:65], s[96:97], 2, v[64:65]
	v_lshl_add_u64 v[64:65], v[64:65], 0, v[130:131]
	s_lshl_b64 s[92:93], s[22:23], 5
	v_lshl_add_u64 v[72:73], v[64:65], 0, s[92:93]
	global_load_dwordx4 v[68:71], v[64:65], off nt
	s_nop 0
	global_load_dwordx4 v[64:67], v[72:73], off nt
	v_lshl_add_u64 v[72:73], v[72:73], 0, s[92:93]
	v_lshl_add_u64 v[80:81], v[72:73], 0, s[92:93]
	global_load_dwordx4 v[76:79], v[72:73], off nt
	s_nop 0
	global_load_dwordx4 v[72:75], v[80:81], off nt
	v_lshl_add_u64 v[80:81], v[80:81], 0, s[92:93]
	v_lshl_add_u64 v[88:89], v[80:81], 0, s[92:93]
	v_lshl_add_u64 v[92:93], v[88:89], 0, s[92:93]
	global_load_dwordx4 v[84:87], v[80:81], off nt
	s_nop 0
	global_load_dwordx4 v[80:83], v[88:89], off nt
	s_cmp_eq_u64 s[88:89], 0
	global_load_dwordx4 v[88:91], v[92:93], off nt
	v_lshl_add_u64 v[92:93], v[92:93], 0, s[92:93]
	global_load_dwordx4 v[92:95], v[92:93], off nt
	s_load_dwordx2 s[92:93], s[94:95], 0x0
	s_cbranch_scc1 .LBB0_179
	v_lshl_add_u64 v[96:97], v[96:97], 2, s[88:89]
	global_load_dword v98, v[96:97], off
	global_load_dword v100, v[96:97], off offset:32
	global_load_dword v102, v[96:97], off offset:64
	global_load_dword v104, v[96:97], off offset:96
	global_load_dword v106, v[96:97], off offset:128
	global_load_dword v108, v[96:97], off offset:160
	global_load_dword v110, v[96:97], off offset:192
	s_nop 0
	global_load_dword v96, v[96:97], off offset:224
	s_waitcnt vmcnt(7)
	v_pk_mul_f32 v[70:71], v[70:71], v[98:99] op_sel_hi:[1,0]
	v_pk_mul_f32 v[68:69], v[68:69], v[98:99] op_sel_hi:[1,0]
	s_waitcnt vmcnt(6)
	v_pk_mul_f32 v[66:67], v[66:67], v[100:101] op_sel_hi:[1,0]
	v_pk_mul_f32 v[64:65], v[64:65], v[100:101] op_sel_hi:[1,0]
	s_waitcnt vmcnt(5)
	v_pk_mul_f32 v[78:79], v[78:79], v[102:103] op_sel_hi:[1,0]
	v_pk_mul_f32 v[76:77], v[76:77], v[102:103] op_sel_hi:[1,0]
	s_waitcnt vmcnt(4)
	v_pk_mul_f32 v[74:75], v[74:75], v[104:105] op_sel_hi:[1,0]
	v_pk_mul_f32 v[72:73], v[72:73], v[104:105] op_sel_hi:[1,0]
	s_waitcnt vmcnt(3)
	v_pk_mul_f32 v[86:87], v[86:87], v[106:107] op_sel_hi:[1,0]
	v_pk_mul_f32 v[84:85], v[84:85], v[106:107] op_sel_hi:[1,0]
	s_waitcnt vmcnt(2)
	v_pk_mul_f32 v[82:83], v[82:83], v[108:109] op_sel_hi:[1,0]
	v_pk_mul_f32 v[80:81], v[80:81], v[108:109] op_sel_hi:[1,0]
	s_waitcnt vmcnt(1)
	v_pk_mul_f32 v[90:91], v[90:91], v[110:111] op_sel_hi:[1,0]
	v_pk_mul_f32 v[88:89], v[88:89], v[110:111] op_sel_hi:[1,0]
	s_waitcnt vmcnt(0)
	v_pk_mul_f32 v[94:95], v[94:95], v[96:97] op_sel_hi:[1,0]
	v_pk_mul_f32 v[92:93], v[92:93], v[96:97] op_sel_hi:[1,0]
; __device__ __forceinline__ TRegs t_load(const TItem& t, int lane) {
;     const int nblk = t.N / 32, kb = t.item / nblk, nb = t.item % nblk, k0 = 64 * kb, n0 = 32 * nb; TRegs r;
;     const float* p = t.W + (size_t)(k0 + (lane >> 3)) * t.N + n0 + 4 * (lane & 7);
; #pragma unroll
;     for (int i = 0; i < 8; ++i) r.v[i] = *(const f32x4*)(p + (size_t)(8 * i) * t.N);
;     if (t.gk) {
; #pragma unroll
;         for (int i = 0; i < 8; ++i) r.v[i] = r.v[i] * t.gk[k0 + (lane >> 3) + 8 * i];
;     }
;     return r;
; }
.LBB0_179:
	s_lshr_b32 s53, s86, 5
	v_cvt_f32_u32_e32 v96, s53
	s_sub_i32 s94, 0, s53
	s_abs_i32 s89, s49
	s_ashr_i32 s88, s49, 31
	v_rcp_iflag_f32_e32 v96, v96
	s_mov_b32 s87, s23
	v_mul_f32_e32 v96, 0x4f7ffffe, v96
	v_cvt_u32_f32_e32 v96, v96
	s_nop 0
	v_readfirstlane_b32 s95, v96
	s_mul_i32 s94, s94, s95
	s_mul_hi_u32 s94, s95, s94
	s_add_i32 s95, s95, s94
	s_mul_hi_u32 s94, s89, s95
	s_mul_i32 s95, s94, s53
	s_sub_i32 s89, s89, s95
	s_add_i32 s96, s94, 1
	s_sub_i32 s95, s89, s53
	s_cmp_ge_u32 s89, s53
	s_cselect_b32 s94, s96, s94
	s_cselect_b32 s89, s95, s89
	s_add_i32 s95, s94, 1
	s_cmp_ge_u32 s89, s53
	s_cselect_b32 s89, s95, s94
	s_xor_b32 s89, s89, s88
	s_sub_i32 s88, s89, s88
	v_lshl_or_b32 v134, s88, 6, v129
	v_mad_u64_u32 v[96:97], s[94:95], v134, s86, 0
	s_mul_i32 s53, s88, s53
	v_ashrrev_i32_e32 v135, 31, v134
	v_mov_b32_e32 v98, v97
	s_sub_i32 s53, s49, s53
	v_mad_u64_u32 v[98:99], s[94:95], v135, s86, v[98:99]
	s_lshl_b32 s88, s53, 5
	v_mov_b32_e32 v97, v98
	s_waitcnt lgkmcnt(0)
	v_lshl_add_u64 v[96:97], v[96:97], 2, s[92:93]
	s_ashr_i32 s89, s88, 31
	v_lshl_add_u64 v[96:97], s[88:89], 2, v[96:97]
	v_lshl_add_u64 v[96:97], v[96:97], 0, v[130:131]
	s_lshl_b64 s[88:89], s[86:87], 5
	v_lshl_add_u64 v[104:105], v[96:97], 0, s[88:89]
	global_load_dwordx4 v[100:103], v[96:97], off nt
	s_nop 0
	global_load_dwordx4 v[96:99], v[104:105], off nt
	v_lshl_add_u64 v[104:105], v[104:105], 0, s[88:89]
	v_lshl_add_u64 v[112:113], v[104:105], 0, s[88:89]
	global_load_dwordx4 v[108:111], v[104:105], off nt
	s_nop 0
	global_load_dwordx4 v[104:107], v[112:113], off nt
	v_lshl_add_u64 v[112:113], v[112:113], 0, s[88:89]
	v_lshl_add_u64 v[120:121], v[112:113], 0, s[88:89]
	v_lshl_add_u64 v[124:125], v[120:121], 0, s[88:89]
	global_load_dwordx4 v[116:119], v[112:113], off nt
	s_nop 0
	global_load_dwordx4 v[112:115], v[120:121], off nt
	s_cmp_eq_u64 s[90:91], 0
	global_load_dwordx4 v[120:123], v[124:125], off nt
	v_lshl_add_u64 v[124:125], v[124:125], 0, s[88:89]
	global_load_dwordx4 v[124:127], v[124:125], off nt
	s_cbranch_scc1 .LBB0_181
	v_lshl_add_u64 v[134:135], v[134:135], 2, s[90:91]
	global_load_dword v142, v[134:135], off
	global_load_dword v144, v[134:135], off offset:32
	global_load_dword v146, v[134:135], off offset:64
	global_load_dword v148, v[134:135], off offset:96
	global_load_dword v150, v[134:135], off offset:128
	global_load_dword v152, v[134:135], off offset:160
	global_load_dword v154, v[134:135], off offset:192
	s_nop 0
	global_load_dword v134, v[134:135], off offset:224
	s_waitcnt vmcnt(7)
	v_pk_mul_f32 v[102:103], v[102:103], v[142:143] op_sel_hi:[1,0]
	v_pk_mul_f32 v[100:101], v[100:101], v[142:143] op_sel_hi:[1,0]
	s_waitcnt vmcnt(6)
	v_pk_mul_f32 v[98:99], v[98:99], v[144:145] op_sel_hi:[1,0]
	v_pk_mul_f32 v[96:97], v[96:97], v[144:145] op_sel_hi:[1,0]
	s_waitcnt vmcnt(5)
	v_pk_mul_f32 v[110:111], v[110:111], v[146:147] op_sel_hi:[1,0]
	v_pk_mul_f32 v[108:109], v[108:109], v[146:147] op_sel_hi:[1,0]
	s_waitcnt vmcnt(4)
	v_pk_mul_f32 v[106:107], v[106:107], v[148:149] op_sel_hi:[1,0]
	v_pk_mul_f32 v[104:105], v[104:105], v[148:149] op_sel_hi:[1,0]
	s_waitcnt vmcnt(3)
	v_pk_mul_f32 v[118:119], v[118:119], v[150:151] op_sel_hi:[1,0]
	v_pk_mul_f32 v[116:117], v[116:117], v[150:151] op_sel_hi:[1,0]
	s_waitcnt vmcnt(2)
	v_pk_mul_f32 v[114:115], v[114:115], v[152:153] op_sel_hi:[1,0]
	v_pk_mul_f32 v[112:113], v[112:113], v[152:153] op_sel_hi:[1,0]
	s_waitcnt vmcnt(1)
	v_pk_mul_f32 v[122:123], v[122:123], v[154:155] op_sel_hi:[1,0]
	v_pk_mul_f32 v[120:121], v[120:121], v[154:155] op_sel_hi:[1,0]
	s_waitcnt vmcnt(0)
	v_pk_mul_f32 v[126:127], v[126:127], v[134:135] op_sel_hi:[1,0]
	v_pk_mul_f32 v[124:125], v[124:125], v[134:135] op_sel_hi:[1,0]

; __device__ __forceinline__ unsigned cvt_pk_bf16(float lo, float hi) { unsigned r; asm volatile("v_cvt_pk_bf16_f32 %0, %1, %2" : "=v"(r) : "v"(lo), "v"(hi)); return r; }
; __device__ __forceinline__ unsigned cvt_pk_bf16(float lo, float hi) { const f32x2 v = {lo, hi}; const bf16x2_t b = __builtin_convertvector(v, bf16x2_t); return __builtin_bit_cast(unsigned, b); }
; __device__ __forceinline__ void p0_prologue(Frame& F) {
;     ...
;     for (int m0 = gw; m0 < MT; m0 += 2 * NGW) {
;         f32x4 v[2][4], pv[2]; int mm[2];
; #pragma unroll
;         for (int q = 0; q < 2; ++q) {
;             const int m = (m0 + q * NGW < MT) ? m0 + q * NGW : m0; mm[q] = m;
;             const float* xrow = (m < MP) ? A.in[0] + (size_t)m * D : A.in[1] + (size_t)(m - MP) * D;
;             const float* prow = (m < MP) ? A.in[2] + (size_t)m * DPLE : A.in[3] + (size_t)(m - MP) * DPLE;
; #pragma unroll
;             for (int j = 0; j < 4; ++j) v[q][j] = *((const f32x4*)xrow + F.lane + 64 * j);
;             pv[q] = *((const f32x4*)prow + F.lane);
;         }
; #pragma unroll
;         for (int q = 0; q < 2; ++q) {
;             const int m = mm[q]; float s = 0.f;
; #pragma unroll
;             for (int j = 0; j < 4; ++j) s += (v[q][j][0] * v[q][j][0] + v[q][j][1] * v[q][j][1]) + (v[q][j][2] * v[q][j][2] + v[q][j][3] * v[q][j][3]);
;             s = wave_sum(s);
;             v2u* o8 = (v2u*)(XB + (size_t)m * D) + F.lane;
; #pragma unroll
;             for (int j = 0; j < 4; ++j) { v2u w; w.x = cvt_pk_bf16(v[q][j][0], v[q][j][1]); w.y = cvt_pk_bf16(v[q][j][2], v[q][j][3]); o8[64 * j] = w; }
;             if (F.lane < 16) SS[(size_t)m * 16 + F.lane] = (F.lane == 0) ? s : 0.f;
;             v2u w; w.x = cvt_pk_bf16(pv[q][0], pv[q][1]); w.y = cvt_pk_bf16(pv[q][2], pv[q][3]);
;             *((v2u*)(PE + (size_t)m * DPLE) + F.lane) = w;
;         }
.LBB0_186:
	s_add_i32 s4, s10, 0xffffc000
	s_ashr_i32 s11, s10, 31
	s_cmpk_lt_i32 s10, 0x4000
	s_cselect_b32 s12, 0, 8
	s_cselect_b32 s5, s11, 0
	s_cselect_b32 s4, s10, s4
	s_cselect_b32 s16, 16, 24
	s_add_u32 s12, s0, s12
	s_addc_u32 s13, s1, 0
	s_load_dwordx2 s[12:13], s[12:13], 0x0
	s_lshl_b64 s[14:15], s[4:5], 12
	s_waitcnt lgkmcnt(0)
	s_add_u32 s12, s12, s14
	s_addc_u32 s13, s13, s15
	global_load_dwordx4 v[38:41], v36, s[12:13] nt
	global_load_dwordx4 v[42:45], v36, s[12:13] offset:1024 nt
	global_load_dwordx4 v[46:49], v36, s[12:13] offset:2048 nt
	global_load_dwordx4 v[50:53], v36, s[12:13] offset:3072 nt
	s_add_u32 s12, s0, s16
	s_addc_u32 s13, s1, 0
	s_load_dwordx2 s[12:13], s[12:13], 0x0
	s_lshl_b64 s[4:5], s[4:5], 10
	s_waitcnt lgkmcnt(0)
	s_add_u32 s14, s12, s4
	s_addc_u32 s15, s13, s5
	s_add_i32 s4, s10, s3
	s_cmpk_lt_i32 s4, 0x4400
	s_cselect_b32 s12, s4, s10
	s_ashr_i32 s13, s12, 31
	s_add_i32 s5, s12, 0xffffc000
	s_cmpk_lt_i32 s12, 0x4000
	s_cselect_b32 s16, s12, s5
	s_cselect_b32 s5, 0, 8
	s_cselect_b32 s17, s13, 0
	s_cselect_b32 s22, 16, 24
	s_add_u32 s18, s0, s5
	s_addc_u32 s19, s1, 0
	s_load_dwordx2 s[18:19], s[18:19], 0x0
	s_lshl_b64 s[20:21], s[16:17], 12
	s_waitcnt lgkmcnt(0)
	s_add_u32 s18, s18, s20
	s_addc_u32 s19, s19, s21
	s_add_u32 s20, s0, s22
	s_addc_u32 s21, s1, 0
	s_load_dwordx2 s[20:21], s[20:21], 0x0
	global_load_dwordx4 v[20:23], v36, s[14:15] nt
	global_load_dwordx4 v[16:19], v36, s[18:19] nt
	global_load_dwordx4 v[12:15], v36, s[18:19] offset:1024 nt
	global_load_dwordx4 v[4:7], v36, s[18:19] offset:2048 nt
	s_lshl_b64 s[14:15], s[16:17], 10
	s_waitcnt lgkmcnt(0)
	s_add_u32 s14, s20, s14
	s_addc_u32 s15, s21, s15
	global_load_dwordx4 v[8:11], v36, s[18:19] offset:3072 nt
	global_load_dwordx4 v[0:3], v36, s[14:15] nt
	s_lshl_b64 s[14:15], s[10:11], 11
	s_waitcnt vmcnt(9)
	v_mul_f32_e32 v37, v39, v39
	v_mul_f32_e32 v54, v41, v41
	s_waitcnt vmcnt(8)
	v_mul_f32_e32 v55, v43, v43
	v_mul_f32_e32 v56, v45, v45
	s_waitcnt vmcnt(7)
	v_mul_f32_e32 v57, v47, v47
	v_mul_f32_e32 v58, v49, v49
	v_fmac_f32_e32 v37, v38, v38
	v_fmac_f32_e32 v54, v40, v40
	v_fmac_f32_e32 v55, v42, v42
	v_fmac_f32_e32 v56, v44, v44
	s_waitcnt vmcnt(6)
	v_mul_f32_e32 v59, v51, v51
	v_mul_f32_e32 v60, v53, v53
	v_fmac_f32_e32 v57, v46, v46
	v_fmac_f32_e32 v58, v48, v48
	v_add_f32_e32 v37, v37, v54
	v_add_f32_e32 v54, v55, v56
	v_fmac_f32_e32 v59, v50, v50
	v_fmac_f32_e32 v60, v52, v52
	v_add_f32_e32 v55, v57, v58
	v_add_f32_e32 v37, v37, v54
	v_add_f32_e32 v56, v59, v60
	v_add_f32_e32 v37, v37, v55
	v_add_f32_e32 v37, v37, v56
	ds_bpermute_b32 v54, v30, v37
	v_cvt_pk_bf16_f32 v38, v38, v39
	v_cvt_pk_bf16_f32 v39, v40, v41
	v_cvt_pk_bf16_f32 v40, v42, v43
	v_cvt_pk_bf16_f32 v41, v44, v45
	s_waitcnt lgkmcnt(0)
	v_add_f32_e32 v37, v37, v54
	ds_bpermute_b32 v54, v31, v37
	v_cvt_pk_bf16_f32 v42, v46, v47
	s_waitcnt lgkmcnt(0)
	v_add_f32_e32 v37, v37, v54
	ds_bpermute_b32 v54, v32, v37
	s_waitcnt lgkmcnt(0)
	v_add_f32_e32 v37, v37, v54
	ds_bpermute_b32 v56, v33, v37
	v_lshl_add_u64 v[54:55], v[24:25], 0, s[14:15]
	global_store_dwordx2 v[54:55], v[38:39], off
	global_store_dwordx2 v[54:55], v[40:41], off offset:512
	v_cvt_pk_bf16_f32 v40, v50, v51
	v_cvt_pk_bf16_f32 v41, v52, v53
	s_waitcnt lgkmcnt(0)
	v_add_f32_e32 v37, v37, v56
	ds_bpermute_b32 v43, v34, v37
	global_store_dwordx2 v[54:55], v[40:41], off offset:1536
	s_waitcnt lgkmcnt(0)
	v_add_f32_e32 v37, v37, v43
	ds_bpermute_b32 v38, v35, v37
	v_cvt_pk_bf16_f32 v43, v48, v49
	global_store_dwordx2 v[54:55], v[42:43], off offset:1024
	s_and_saveexec_b64 s[14:15], vcc
	s_cbranch_execz .LBB0_188
	s_waitcnt lgkmcnt(0)
	v_add_f32_e32 v37, v37, v38
	s_lshl_b64 s[16:17], s[10:11], 6
	v_lshl_add_u64 v[38:39], v[26:27], 0, s[16:17]
	v_cndmask_b32_e64 v37, 0, v37, s[6:7]
	global_store_dword v[38:39], v37, off
